# baseline (speedup 1.0000x reference)
.LBB0_160:
	v_readlane_b32 s98, v255, 6
	v_readlane_b32 s99, v254, 40
	s_add_i32 s98, s0, s98
	s_cmp_ge_i32 s98, s99
	s_cbranch_scc1 .Lgu_slow
	v_mfma_f32_32x32x16_bf16 a[16:31], v[132:135], v[112:115], a[16:31]
	v_mfma_f32_32x32x16_bf16 a[32:47], v[132:135], v[80:83], a[32:47]
	v_mfma_f32_32x32x16_bf16 a[0:15], v[132:135], v[128:131], a[0:15]
	v_or_b32_e32 v129, s2, v161
	v_or_b32_e32 v128, s1, v162
	v_add_u32_e32 v133, v163, v129
	v_readlane_b32 s2, v253, 61
	v_readlane_b32 s3, v253, 62
	v_ashrrev_i32_e32 v130, 1, v128
	s_nop 0
	v_mov_b64_e32 v[128:129], s[2:3]
	s_movk_i32 s1, 0x1600
	v_mad_i64_i32 v[134:135], s[2:3], v133, s1, v[128:129]
	v_ashrrev_i32_e32 v131, 31, v130
	v_lshlrev_b64 v[130:131], 1, v[130:131]
	v_lshl_add_u64 v[96:97], v[134:135], 0, v[130:131]
	v_and_b32_e32 v192, 32, v160
	v_lshl_add_u64 v[96:97], v[96:97], 0, v[192:193]
	v_add_u32_e32 v136, 32, v133
	v_mad_i64_i32 v[136:137], s[4:5], v136, s1, v[128:129]
	v_lshl_add_u64 v[136:137], v[136:137], 0, v[130:131]
	v_lshl_add_u64 v[66:67], v[136:137], 0, v[192:193]
	v_add_u32_e32 v100, 64, v133
	v_mad_i64_i32 v[100:101], s[4:5], v100, s1, v[128:129]
	v_lshl_add_u64 v[100:101], v[100:101], 0, v[130:131]
	v_lshl_add_u64 v[64:65], v[100:101], 0, v[192:193]
	v_mov_b32_e32 v154, 0xbfb8aa3b
	v_mov_b32_e32 v155, 0xbfb8aa3b
	v_accvgpr_read_b32 v0, a80
	v_accvgpr_read_b32 v1, a81
	v_accvgpr_read_b32 v2, a82
	v_accvgpr_read_b32 v3, a83
	v_accvgpr_read_b32 v4, a84
	v_accvgpr_read_b32 v5, a85
	v_accvgpr_read_b32 v6, a86
	v_accvgpr_read_b32 v7, a87
	v_accvgpr_read_b32 v8, a88
	v_accvgpr_read_b32 v9, a89
	v_accvgpr_read_b32 v10, a90
	v_accvgpr_read_b32 v11, a91
	v_accvgpr_read_b32 v12, a92
	v_accvgpr_read_b32 v13, a93
	v_accvgpr_read_b32 v14, a94
	v_accvgpr_read_b32 v15, a95
	v_mul_f32_e32 v32, 0xbfb8aa3b, v0
	v_mul_f32_e32 v33, 0xbfb8aa3b, v1
	v_mul_f32_e32 v34, 0xbfb8aa3b, v2
	v_mul_f32_e32 v35, 0xbfb8aa3b, v3
	v_mul_f32_e32 v36, 0xbfb8aa3b, v4
	v_mul_f32_e32 v37, 0xbfb8aa3b, v5
	v_mul_f32_e32 v38, 0xbfb8aa3b, v6
	v_mul_f32_e32 v39, 0xbfb8aa3b, v7
	v_mul_f32_e32 v40, 0xbfb8aa3b, v8
	v_mul_f32_e32 v41, 0xbfb8aa3b, v9
	v_mul_f32_e32 v42, 0xbfb8aa3b, v10
	v_mul_f32_e32 v43, 0xbfb8aa3b, v11
	v_mul_f32_e32 v44, 0xbfb8aa3b, v12
	v_mul_f32_e32 v45, 0xbfb8aa3b, v13
	v_mul_f32_e32 v46, 0xbfb8aa3b, v14
	v_mul_f32_e32 v47, 0xbfb8aa3b, v15
	v_accvgpr_read_b32 v16, a96
	v_accvgpr_read_b32 v17, a97
	v_accvgpr_read_b32 v18, a98
	v_accvgpr_read_b32 v19, a99
	v_accvgpr_read_b32 v20, a100
	v_accvgpr_read_b32 v21, a101
	v_accvgpr_read_b32 v22, a102
	v_accvgpr_read_b32 v23, a103
	v_accvgpr_read_b32 v24, a104
	v_accvgpr_read_b32 v25, a105
	v_accvgpr_read_b32 v26, a106
	v_accvgpr_read_b32 v27, a107
	v_accvgpr_read_b32 v28, a108
	v_accvgpr_read_b32 v29, a109
	v_accvgpr_read_b32 v30, a110
	v_accvgpr_read_b32 v31, a111
	v_exp_f32_e32 v32, v32
	v_exp_f32_e32 v33, v33
	v_exp_f32_e32 v34, v34
	v_exp_f32_e32 v35, v35
	v_exp_f32_e32 v36, v36
	v_exp_f32_e32 v37, v37
	v_exp_f32_e32 v38, v38
	v_exp_f32_e32 v39, v39
	v_exp_f32_e32 v40, v40
	v_exp_f32_e32 v41, v41
	v_exp_f32_e32 v42, v42
	v_exp_f32_e32 v43, v43
	v_exp_f32_e32 v44, v44
	v_exp_f32_e32 v45, v45
	v_exp_f32_e32 v46, v46
	v_exp_f32_e32 v47, v47
	s_nop 0
	v_add_f32_e32 v32, 1.0, v32
	v_add_f32_e32 v33, 1.0, v33
	v_add_f32_e32 v34, 1.0, v34
	v_add_f32_e32 v35, 1.0, v35
	v_add_f32_e32 v36, 1.0, v36
	v_add_f32_e32 v37, 1.0, v37
	v_add_f32_e32 v38, 1.0, v38
	v_add_f32_e32 v39, 1.0, v39
	v_add_f32_e32 v40, 1.0, v40
	v_add_f32_e32 v41, 1.0, v41
	v_add_f32_e32 v42, 1.0, v42
	v_add_f32_e32 v43, 1.0, v43
	v_add_f32_e32 v44, 1.0, v44
	v_add_f32_e32 v45, 1.0, v45
	v_add_f32_e32 v46, 1.0, v46
	v_add_f32_e32 v47, 1.0, v47
	v_rcp_f32_e32 v32, v32
	v_rcp_f32_e32 v33, v33
	v_rcp_f32_e32 v34, v34
	v_rcp_f32_e32 v35, v35
	v_rcp_f32_e32 v36, v36
	v_rcp_f32_e32 v37, v37
	v_rcp_f32_e32 v38, v38
	v_rcp_f32_e32 v39, v39
	v_rcp_f32_e32 v40, v40
	v_rcp_f32_e32 v41, v41
	v_rcp_f32_e32 v42, v42
	v_rcp_f32_e32 v43, v43
	v_rcp_f32_e32 v44, v44
	v_rcp_f32_e32 v45, v45
	v_rcp_f32_e32 v46, v46
	v_rcp_f32_e32 v47, v47
	s_nop 0
	v_mul_f32_e32 v32, v0, v32
	v_mul_f32_e32 v33, v1, v33
	v_mul_f32_e32 v34, v2, v34
	v_mul_f32_e32 v35, v3, v35
	v_mul_f32_e32 v36, v4, v36
	v_mul_f32_e32 v37, v5, v37
	v_mul_f32_e32 v38, v6, v38
	v_mul_f32_e32 v39, v7, v39
	v_mul_f32_e32 v40, v8, v40
	v_mul_f32_e32 v41, v9, v41
	v_mul_f32_e32 v42, v10, v42
	v_mul_f32_e32 v43, v11, v43
	v_mul_f32_e32 v44, v12, v44
	v_mul_f32_e32 v45, v13, v45
	v_mul_f32_e32 v46, v14, v46
	v_mul_f32_e32 v47, v15, v47
	v_mul_f32_e32 v32, v32, v16
	v_mul_f32_e32 v33, v33, v17
	v_mul_f32_e32 v34, v34, v18
	v_mul_f32_e32 v35, v35, v19
	v_mul_f32_e32 v36, v36, v20
	v_mul_f32_e32 v37, v37, v21
	v_mul_f32_e32 v38, v38, v22
	v_mul_f32_e32 v39, v39, v23
	v_mul_f32_e32 v40, v40, v24
	v_mul_f32_e32 v41, v41, v25
	v_mul_f32_e32 v42, v42, v26
	v_mul_f32_e32 v43, v43, v27
	v_mul_f32_e32 v44, v44, v28
	v_mul_f32_e32 v45, v45, v29
	v_mul_f32_e32 v46, v46, v30
	v_mul_f32_e32 v47, v47, v31
	v_cvt_pk_bf16_f32 v48, v32, v33
	v_cvt_pk_bf16_f32 v49, v34, v35
	v_cvt_pk_bf16_f32 v52, v36, v37
	v_cvt_pk_bf16_f32 v53, v38, v39
	v_cvt_pk_bf16_f32 v50, v40, v41
	v_cvt_pk_bf16_f32 v51, v42, v43
	v_cvt_pk_bf16_f32 v54, v44, v45
	v_cvt_pk_bf16_f32 v55, v46, v47
	s_nop 1
	v_permlane32_swap_b32_e32 v48, v50
	v_permlane32_swap_b32_e32 v49, v51
	v_permlane32_swap_b32_e32 v52, v54
	v_permlane32_swap_b32_e32 v53, v55
	s_nop 1
	global_store_dwordx4 v[96:97], v[48:51], off
	global_store_dwordx4 v[96:97], v[52:55], off offset:16
	v_accvgpr_read_b32 v68, a48
	v_accvgpr_read_b32 v69, a49
	v_accvgpr_read_b32 v70, a50
	v_accvgpr_read_b32 v71, a51
	v_accvgpr_read_b32 v72, a52
	v_accvgpr_read_b32 v73, a53
	v_accvgpr_read_b32 v74, a54
	v_accvgpr_read_b32 v75, a55
	v_accvgpr_read_b32 v76, a56
	v_accvgpr_read_b32 v77, a57
	v_accvgpr_read_b32 v78, a58
	v_accvgpr_read_b32 v79, a59
	v_accvgpr_read_b32 v80, a60
	v_accvgpr_read_b32 v81, a61
	v_accvgpr_read_b32 v82, a62
	v_accvgpr_read_b32 v83, a63
	v_mul_f32_e32 v138, 0xbfb8aa3b, v68
	v_mul_f32_e32 v139, 0xbfb8aa3b, v69
	v_mul_f32_e32 v140, 0xbfb8aa3b, v70
	v_mul_f32_e32 v141, 0xbfb8aa3b, v71
	v_mul_f32_e32 v142, 0xbfb8aa3b, v72
	v_mul_f32_e32 v143, 0xbfb8aa3b, v73
	v_mul_f32_e32 v144, 0xbfb8aa3b, v74
	v_mul_f32_e32 v145, 0xbfb8aa3b, v75
	v_mul_f32_e32 v146, 0xbfb8aa3b, v76
	v_mul_f32_e32 v147, 0xbfb8aa3b, v77
	v_mul_f32_e32 v148, 0xbfb8aa3b, v78
	v_mul_f32_e32 v149, 0xbfb8aa3b, v79
	v_mul_f32_e32 v150, 0xbfb8aa3b, v80
	v_mul_f32_e32 v151, 0xbfb8aa3b, v81
	v_mul_f32_e32 v152, 0xbfb8aa3b, v82
	v_mul_f32_e32 v153, 0xbfb8aa3b, v83
	v_accvgpr_read_b32 v104, a112
	v_accvgpr_read_b32 v105, a113
	v_accvgpr_read_b32 v106, a114
	v_accvgpr_read_b32 v107, a115
	v_accvgpr_read_b32 v108, a116
	v_accvgpr_read_b32 v109, a117
	v_accvgpr_read_b32 v110, a118
	v_accvgpr_read_b32 v111, a119
	v_accvgpr_read_b32 v112, a120
	v_accvgpr_read_b32 v113, a121
	v_accvgpr_read_b32 v114, a122
	v_accvgpr_read_b32 v115, a123
	v_accvgpr_read_b32 v116, a124
	v_accvgpr_read_b32 v117, a125
	v_accvgpr_read_b32 v118, a126
	v_accvgpr_read_b32 v119, a127
	v_exp_f32_e32 v138, v138
	v_exp_f32_e32 v139, v139
	v_exp_f32_e32 v140, v140
	v_exp_f32_e32 v141, v141
	v_exp_f32_e32 v142, v142
	v_exp_f32_e32 v143, v143
	v_exp_f32_e32 v144, v144
	v_exp_f32_e32 v145, v145
	v_exp_f32_e32 v146, v146
	v_exp_f32_e32 v147, v147
	v_exp_f32_e32 v148, v148
	v_exp_f32_e32 v149, v149
	v_exp_f32_e32 v150, v150
	v_exp_f32_e32 v151, v151
	v_exp_f32_e32 v152, v152
	v_exp_f32_e32 v153, v153
	s_nop 0
	v_add_f32_e32 v138, 1.0, v138
	v_add_f32_e32 v139, 1.0, v139
	v_add_f32_e32 v140, 1.0, v140
	v_add_f32_e32 v141, 1.0, v141
	v_add_f32_e32 v142, 1.0, v142
	v_add_f32_e32 v143, 1.0, v143
	v_add_f32_e32 v144, 1.0, v144
	v_add_f32_e32 v145, 1.0, v145
	v_add_f32_e32 v146, 1.0, v146
	v_add_f32_e32 v147, 1.0, v147
	v_add_f32_e32 v148, 1.0, v148
	v_add_f32_e32 v149, 1.0, v149
	v_add_f32_e32 v150, 1.0, v150
	v_add_f32_e32 v151, 1.0, v151
	v_add_f32_e32 v152, 1.0, v152
	v_add_f32_e32 v153, 1.0, v153
	v_rcp_f32_e32 v138, v138
	v_rcp_f32_e32 v139, v139
	v_rcp_f32_e32 v140, v140
	v_rcp_f32_e32 v141, v141
	v_rcp_f32_e32 v142, v142
	v_rcp_f32_e32 v143, v143
	v_rcp_f32_e32 v144, v144
	v_rcp_f32_e32 v145, v145
	v_rcp_f32_e32 v146, v146
	v_rcp_f32_e32 v147, v147
	v_rcp_f32_e32 v148, v148
	v_rcp_f32_e32 v149, v149
	v_rcp_f32_e32 v150, v150
	v_rcp_f32_e32 v151, v151
	v_rcp_f32_e32 v152, v152
	v_rcp_f32_e32 v153, v153
	s_nop 0
	v_mul_f32_e32 v138, v68, v138
	v_mul_f32_e32 v139, v69, v139
	v_mul_f32_e32 v140, v70, v140
	v_mul_f32_e32 v141, v71, v141
	v_mul_f32_e32 v142, v72, v142
	v_mul_f32_e32 v143, v73, v143
	v_mul_f32_e32 v144, v74, v144
	v_mul_f32_e32 v145, v75, v145
	v_mul_f32_e32 v146, v76, v146
	v_mul_f32_e32 v147, v77, v147
	v_mul_f32_e32 v148, v78, v148
	v_mul_f32_e32 v149, v79, v149
	v_mul_f32_e32 v150, v80, v150
	v_mul_f32_e32 v151, v81, v151
	v_mul_f32_e32 v152, v82, v152
	v_mul_f32_e32 v153, v83, v153
	v_mul_f32_e32 v138, v138, v104
	v_mul_f32_e32 v139, v139, v105
	v_mul_f32_e32 v140, v140, v106
	v_mul_f32_e32 v141, v141, v107
	v_mul_f32_e32 v142, v142, v108
	v_mul_f32_e32 v143, v143, v109
	v_mul_f32_e32 v144, v144, v110
	v_mul_f32_e32 v145, v145, v111
	v_mul_f32_e32 v146, v146, v112
	v_mul_f32_e32 v147, v147, v113
	v_mul_f32_e32 v148, v148, v114
	v_mul_f32_e32 v149, v149, v115
	v_mul_f32_e32 v150, v150, v116
	v_mul_f32_e32 v151, v151, v117
	v_mul_f32_e32 v152, v152, v118
	v_mul_f32_e32 v153, v153, v119
	v_cvt_pk_bf16_f32 v56, v138, v139
	v_cvt_pk_bf16_f32 v57, v140, v141
	v_cvt_pk_bf16_f32 v60, v142, v143
	v_cvt_pk_bf16_f32 v61, v144, v145
	v_cvt_pk_bf16_f32 v58, v146, v147
	v_cvt_pk_bf16_f32 v59, v148, v149
	v_cvt_pk_bf16_f32 v62, v150, v151
	v_cvt_pk_bf16_f32 v63, v152, v153
	s_nop 1
	v_permlane32_swap_b32_e32 v56, v58
	v_permlane32_swap_b32_e32 v57, v59
	v_permlane32_swap_b32_e32 v60, v62
	v_permlane32_swap_b32_e32 v61, v63
	s_nop 1
	global_store_dwordx4 v[66:67], v[56:59], off
	global_store_dwordx4 v[66:67], v[60:63], off offset:16
	v_accvgpr_read_b32 v0, a64
	v_accvgpr_read_b32 v1, a65
	v_accvgpr_read_b32 v2, a66
	v_accvgpr_read_b32 v3, a67
	v_accvgpr_read_b32 v4, a68
	v_accvgpr_read_b32 v5, a69
	v_accvgpr_read_b32 v6, a70
	v_accvgpr_read_b32 v7, a71
	v_accvgpr_read_b32 v8, a72
	v_accvgpr_read_b32 v9, a73
	v_accvgpr_read_b32 v10, a74
	v_accvgpr_read_b32 v11, a75
	v_accvgpr_read_b32 v12, a76
	v_accvgpr_read_b32 v13, a77
	v_accvgpr_read_b32 v14, a78
	v_accvgpr_read_b32 v15, a79
	v_mul_f32_e32 v32, 0xbfb8aa3b, v0
	v_mul_f32_e32 v33, 0xbfb8aa3b, v1
	v_mul_f32_e32 v34, 0xbfb8aa3b, v2
	v_mul_f32_e32 v35, 0xbfb8aa3b, v3
	v_mul_f32_e32 v36, 0xbfb8aa3b, v4
	v_mul_f32_e32 v37, 0xbfb8aa3b, v5
	v_mul_f32_e32 v38, 0xbfb8aa3b, v6
	v_mul_f32_e32 v39, 0xbfb8aa3b, v7
	v_mul_f32_e32 v40, 0xbfb8aa3b, v8
	v_mul_f32_e32 v41, 0xbfb8aa3b, v9
	v_mul_f32_e32 v42, 0xbfb8aa3b, v10
	v_mul_f32_e32 v43, 0xbfb8aa3b, v11
	v_mul_f32_e32 v44, 0xbfb8aa3b, v12
	v_mul_f32_e32 v45, 0xbfb8aa3b, v13
	v_mul_f32_e32 v46, 0xbfb8aa3b, v14
	v_mul_f32_e32 v47, 0xbfb8aa3b, v15
	v_accvgpr_read_b32 v16, a128
	v_accvgpr_read_b32 v17, a129
	v_accvgpr_read_b32 v18, a130
	v_accvgpr_read_b32 v19, a131
	v_accvgpr_read_b32 v20, a132
	v_accvgpr_read_b32 v21, a133
	v_accvgpr_read_b32 v22, a134
	v_accvgpr_read_b32 v23, a135
	v_accvgpr_read_b32 v24, a136
	v_accvgpr_read_b32 v25, a137
	v_accvgpr_read_b32 v26, a138
	v_accvgpr_read_b32 v27, a139
	v_accvgpr_read_b32 v28, a140
	v_accvgpr_read_b32 v29, a141
	v_accvgpr_read_b32 v30, a142
	v_accvgpr_read_b32 v31, a143
	v_exp_f32_e32 v32, v32
	v_exp_f32_e32 v33, v33
	v_exp_f32_e32 v34, v34
	v_exp_f32_e32 v35, v35
	v_exp_f32_e32 v36, v36
	v_exp_f32_e32 v37, v37
	v_exp_f32_e32 v38, v38
	v_exp_f32_e32 v39, v39
	v_exp_f32_e32 v40, v40
	v_exp_f32_e32 v41, v41
	v_exp_f32_e32 v42, v42
	v_exp_f32_e32 v43, v43
	v_exp_f32_e32 v44, v44
	v_exp_f32_e32 v45, v45
	v_exp_f32_e32 v46, v46
	v_exp_f32_e32 v47, v47
	s_nop 0
	v_add_f32_e32 v32, 1.0, v32
	v_add_f32_e32 v33, 1.0, v33
	v_add_f32_e32 v34, 1.0, v34
	v_add_f32_e32 v35, 1.0, v35
	v_add_f32_e32 v36, 1.0, v36
	v_add_f32_e32 v37, 1.0, v37
	v_add_f32_e32 v38, 1.0, v38
	v_add_f32_e32 v39, 1.0, v39
	v_add_f32_e32 v40, 1.0, v40
	v_add_f32_e32 v41, 1.0, v41
	v_add_f32_e32 v42, 1.0, v42
	v_add_f32_e32 v43, 1.0, v43
	v_add_f32_e32 v44, 1.0, v44
	v_add_f32_e32 v45, 1.0, v45
	v_add_f32_e32 v46, 1.0, v46
	v_add_f32_e32 v47, 1.0, v47
	v_rcp_f32_e32 v32, v32
	v_rcp_f32_e32 v33, v33
	v_rcp_f32_e32 v34, v34
	v_rcp_f32_e32 v35, v35
	v_rcp_f32_e32 v36, v36
	v_rcp_f32_e32 v37, v37
	v_rcp_f32_e32 v38, v38
	v_rcp_f32_e32 v39, v39
	v_rcp_f32_e32 v40, v40
	v_rcp_f32_e32 v41, v41
	v_rcp_f32_e32 v42, v42
	v_rcp_f32_e32 v43, v43
	v_rcp_f32_e32 v44, v44
	v_rcp_f32_e32 v45, v45
	v_rcp_f32_e32 v46, v46
	v_rcp_f32_e32 v47, v47
	s_nop 0
	v_mul_f32_e32 v32, v0, v32
	v_mul_f32_e32 v33, v1, v33
	v_mul_f32_e32 v34, v2, v34
	v_mul_f32_e32 v35, v3, v35
	v_mul_f32_e32 v36, v4, v36
	v_mul_f32_e32 v37, v5, v37
	v_mul_f32_e32 v38, v6, v38
	v_mul_f32_e32 v39, v7, v39
	v_mul_f32_e32 v40, v8, v40
	v_mul_f32_e32 v41, v9, v41
	v_mul_f32_e32 v42, v10, v42
	v_mul_f32_e32 v43, v11, v43
	v_mul_f32_e32 v44, v12, v44
	v_mul_f32_e32 v45, v13, v45
	v_mul_f32_e32 v46, v14, v46
	v_mul_f32_e32 v47, v15, v47
	v_mul_f32_e32 v32, v32, v16
	v_mul_f32_e32 v33, v33, v17
	v_mul_f32_e32 v34, v34, v18
	v_mul_f32_e32 v35, v35, v19
	v_mul_f32_e32 v36, v36, v20
	v_mul_f32_e32 v37, v37, v21
	v_mul_f32_e32 v38, v38, v22
	v_mul_f32_e32 v39, v39, v23
	v_mul_f32_e32 v40, v40, v24
	v_mul_f32_e32 v41, v41, v25
	v_mul_f32_e32 v42, v42, v26
	v_mul_f32_e32 v43, v43, v27
	v_mul_f32_e32 v44, v44, v28
	v_mul_f32_e32 v45, v45, v29
	v_mul_f32_e32 v46, v46, v30
	v_mul_f32_e32 v47, v47, v31
	v_cvt_pk_bf16_f32 v48, v32, v33
	v_cvt_pk_bf16_f32 v49, v34, v35
	v_cvt_pk_bf16_f32 v52, v36, v37
	v_cvt_pk_bf16_f32 v53, v38, v39
	v_cvt_pk_bf16_f32 v50, v40, v41
	v_cvt_pk_bf16_f32 v51, v42, v43
	v_cvt_pk_bf16_f32 v54, v44, v45
	v_cvt_pk_bf16_f32 v55, v46, v47
	s_nop 1
	v_permlane32_swap_b32_e32 v48, v50
	v_permlane32_swap_b32_e32 v49, v51
	v_permlane32_swap_b32_e32 v52, v54
	v_permlane32_swap_b32_e32 v53, v55
	s_nop 1
	global_store_dwordx4 v[64:65], v[48:51], off
	global_store_dwordx4 v[64:65], v[52:55], off offset:16
	v_accvgpr_read_b32 v68, a144
	v_accvgpr_read_b32 v69, a145
	v_accvgpr_read_b32 v70, a146
	v_accvgpr_read_b32 v71, a147
	v_accvgpr_read_b32 v72, a148
	v_accvgpr_read_b32 v73, a149
	v_accvgpr_read_b32 v74, a150
	v_accvgpr_read_b32 v75, a151
	v_accvgpr_read_b32 v76, a152
	v_accvgpr_read_b32 v77, a153
	v_accvgpr_read_b32 v78, a154
	v_accvgpr_read_b32 v79, a155
	v_accvgpr_read_b32 v80, a156
	v_accvgpr_read_b32 v81, a157
	v_accvgpr_read_b32 v82, a158
	v_accvgpr_read_b32 v83, a159
	v_mul_f32_e32 v138, 0xbfb8aa3b, v68
	v_mul_f32_e32 v139, 0xbfb8aa3b, v69
	v_mul_f32_e32 v140, 0xbfb8aa3b, v70
	v_mul_f32_e32 v141, 0xbfb8aa3b, v71
	v_mul_f32_e32 v142, 0xbfb8aa3b, v72
	v_mul_f32_e32 v143, 0xbfb8aa3b, v73
	v_mul_f32_e32 v144, 0xbfb8aa3b, v74
	v_mul_f32_e32 v145, 0xbfb8aa3b, v75
	v_mul_f32_e32 v146, 0xbfb8aa3b, v76
	v_mul_f32_e32 v147, 0xbfb8aa3b, v77
	v_mul_f32_e32 v148, 0xbfb8aa3b, v78
	v_mul_f32_e32 v149, 0xbfb8aa3b, v79
	v_mul_f32_e32 v150, 0xbfb8aa3b, v80
	v_mul_f32_e32 v151, 0xbfb8aa3b, v81
	v_mul_f32_e32 v152, 0xbfb8aa3b, v82
	v_mul_f32_e32 v153, 0xbfb8aa3b, v83
	v_accvgpr_read_b32 v104, a32
	v_accvgpr_read_b32 v105, a33
	v_accvgpr_read_b32 v106, a34
	v_accvgpr_read_b32 v107, a35
	v_accvgpr_read_b32 v108, a36
	v_accvgpr_read_b32 v109, a37
	v_accvgpr_read_b32 v110, a38
	v_accvgpr_read_b32 v111, a39
	v_accvgpr_read_b32 v112, a40
	v_accvgpr_read_b32 v113, a41
	v_accvgpr_read_b32 v114, a42
	v_accvgpr_read_b32 v115, a43
	v_accvgpr_read_b32 v116, a44
	v_accvgpr_read_b32 v117, a45
	v_accvgpr_read_b32 v118, a46
	v_accvgpr_read_b32 v119, a47
	v_exp_f32_e32 v138, v138
	v_exp_f32_e32 v139, v139
	v_exp_f32_e32 v140, v140
	v_exp_f32_e32 v141, v141
	v_exp_f32_e32 v142, v142
	v_exp_f32_e32 v143, v143
	v_exp_f32_e32 v144, v144
	v_exp_f32_e32 v145, v145
	v_exp_f32_e32 v146, v146
	v_exp_f32_e32 v147, v147
	v_exp_f32_e32 v148, v148
	v_exp_f32_e32 v149, v149
	v_exp_f32_e32 v150, v150
	v_exp_f32_e32 v151, v151
	v_exp_f32_e32 v152, v152
	v_exp_f32_e32 v153, v153
	s_nop 0
	v_add_f32_e32 v138, 1.0, v138
	v_add_f32_e32 v139, 1.0, v139
	v_add_f32_e32 v140, 1.0, v140
	v_add_f32_e32 v141, 1.0, v141
	v_add_f32_e32 v142, 1.0, v142
	v_add_f32_e32 v143, 1.0, v143
	v_add_f32_e32 v144, 1.0, v144
	v_add_f32_e32 v145, 1.0, v145
	v_add_f32_e32 v146, 1.0, v146
	v_add_f32_e32 v147, 1.0, v147
	v_add_f32_e32 v148, 1.0, v148
	v_add_f32_e32 v149, 1.0, v149
	v_add_f32_e32 v150, 1.0, v150
	v_add_f32_e32 v151, 1.0, v151
	v_add_f32_e32 v152, 1.0, v152
	v_add_f32_e32 v153, 1.0, v153
	v_rcp_f32_e32 v138, v138
	v_rcp_f32_e32 v139, v139
	v_rcp_f32_e32 v140, v140
	v_rcp_f32_e32 v141, v141
	v_rcp_f32_e32 v142, v142
	v_rcp_f32_e32 v143, v143
	v_rcp_f32_e32 v144, v144
	v_rcp_f32_e32 v145, v145
	v_rcp_f32_e32 v146, v146
	v_rcp_f32_e32 v147, v147
	v_rcp_f32_e32 v148, v148
	v_rcp_f32_e32 v149, v149
	v_rcp_f32_e32 v150, v150
	v_rcp_f32_e32 v151, v151
	v_rcp_f32_e32 v152, v152
	v_rcp_f32_e32 v153, v153
	s_nop 0
	v_mul_f32_e32 v138, v68, v138
	v_mul_f32_e32 v139, v69, v139
	v_mul_f32_e32 v140, v70, v140
	v_mul_f32_e32 v141, v71, v141
	v_mul_f32_e32 v142, v72, v142
	v_mul_f32_e32 v143, v73, v143
	v_mul_f32_e32 v144, v74, v144
	v_mul_f32_e32 v145, v75, v145
	v_mul_f32_e32 v146, v76, v146
	v_mul_f32_e32 v147, v77, v147
	v_mul_f32_e32 v148, v78, v148
	v_mul_f32_e32 v149, v79, v149
	v_mul_f32_e32 v150, v80, v150
	v_mul_f32_e32 v151, v81, v151
	v_mul_f32_e32 v152, v82, v152
	v_mul_f32_e32 v153, v83, v153
	v_mul_f32_e32 v138, v138, v104
	v_mul_f32_e32 v139, v139, v105
	v_mul_f32_e32 v140, v140, v106
	v_mul_f32_e32 v141, v141, v107
	v_mul_f32_e32 v142, v142, v108
	v_mul_f32_e32 v143, v143, v109
	v_mul_f32_e32 v144, v144, v110
	v_mul_f32_e32 v145, v145, v111
	v_mul_f32_e32 v146, v146, v112
	v_mul_f32_e32 v147, v147, v113
	v_mul_f32_e32 v148, v148, v114
	v_mul_f32_e32 v149, v149, v115
	v_mul_f32_e32 v150, v150, v116
	v_mul_f32_e32 v151, v151, v117
	v_mul_f32_e32 v152, v152, v118
	v_mul_f32_e32 v153, v153, v119
	v_cvt_pk_bf16_f32 v56, v138, v139
	v_cvt_pk_bf16_f32 v57, v140, v141
	v_cvt_pk_bf16_f32 v60, v142, v143
	v_cvt_pk_bf16_f32 v61, v144, v145
	v_cvt_pk_bf16_f32 v58, v146, v147
	v_cvt_pk_bf16_f32 v59, v148, v149
	v_cvt_pk_bf16_f32 v62, v150, v151
	v_cvt_pk_bf16_f32 v63, v152, v153
	s_nop 1
	v_permlane32_swap_b32_e32 v56, v58
	v_permlane32_swap_b32_e32 v57, v59
	v_permlane32_swap_b32_e32 v60, v62
	v_permlane32_swap_b32_e32 v61, v63
	s_nop 1
	global_store_dwordx4 v[96:97], v[56:59], off offset:64
	global_store_dwordx4 v[96:97], v[60:63], off offset:80
	v_accvgpr_read_b32 v0, a160
	v_accvgpr_read_b32 v1, a161
	v_accvgpr_read_b32 v2, a162
	v_accvgpr_read_b32 v3, a163
	v_accvgpr_read_b32 v4, a164
	v_accvgpr_read_b32 v5, a165
	v_accvgpr_read_b32 v6, a166
	v_accvgpr_read_b32 v7, a167
	v_accvgpr_read_b32 v8, a168
	v_accvgpr_read_b32 v9, a169
	v_accvgpr_read_b32 v10, a170
	v_accvgpr_read_b32 v11, a171
	v_accvgpr_read_b32 v12, a172
	v_accvgpr_read_b32 v13, a173
	v_accvgpr_read_b32 v14, a174
	v_accvgpr_read_b32 v15, a175
	v_mul_f32_e32 v32, 0xbfb8aa3b, v0
	v_mul_f32_e32 v33, 0xbfb8aa3b, v1
	v_mul_f32_e32 v34, 0xbfb8aa3b, v2
	v_mul_f32_e32 v35, 0xbfb8aa3b, v3
	v_mul_f32_e32 v36, 0xbfb8aa3b, v4
	v_mul_f32_e32 v37, 0xbfb8aa3b, v5
	v_mul_f32_e32 v38, 0xbfb8aa3b, v6
	v_mul_f32_e32 v39, 0xbfb8aa3b, v7
	v_mul_f32_e32 v40, 0xbfb8aa3b, v8
	v_mul_f32_e32 v41, 0xbfb8aa3b, v9
	v_mul_f32_e32 v42, 0xbfb8aa3b, v10
	v_mul_f32_e32 v43, 0xbfb8aa3b, v11
	v_mul_f32_e32 v44, 0xbfb8aa3b, v12
	v_mul_f32_e32 v45, 0xbfb8aa3b, v13
	v_mul_f32_e32 v46, 0xbfb8aa3b, v14
	v_mul_f32_e32 v47, 0xbfb8aa3b, v15
	v_accvgpr_read_b32 v16, a16
	v_accvgpr_read_b32 v17, a17
	v_accvgpr_read_b32 v18, a18
	v_accvgpr_read_b32 v19, a19
	v_accvgpr_read_b32 v20, a20
	v_accvgpr_read_b32 v21, a21
	v_accvgpr_read_b32 v22, a22
	v_accvgpr_read_b32 v23, a23
	v_accvgpr_read_b32 v24, a24
	v_accvgpr_read_b32 v25, a25
	v_accvgpr_read_b32 v26, a26
	v_accvgpr_read_b32 v27, a27
	v_accvgpr_read_b32 v28, a28
	v_accvgpr_read_b32 v29, a29
	v_accvgpr_read_b32 v30, a30
	v_accvgpr_read_b32 v31, a31
	v_exp_f32_e32 v32, v32
	v_exp_f32_e32 v33, v33
	v_exp_f32_e32 v34, v34
	v_exp_f32_e32 v35, v35
	v_exp_f32_e32 v36, v36
	v_exp_f32_e32 v37, v37
	v_exp_f32_e32 v38, v38
	v_exp_f32_e32 v39, v39
	v_exp_f32_e32 v40, v40
	v_exp_f32_e32 v41, v41
	v_exp_f32_e32 v42, v42
	v_exp_f32_e32 v43, v43
	v_exp_f32_e32 v44, v44
	v_exp_f32_e32 v45, v45
	v_exp_f32_e32 v46, v46
	v_exp_f32_e32 v47, v47
	s_nop 0
	v_add_f32_e32 v32, 1.0, v32
	v_add_f32_e32 v33, 1.0, v33
	v_add_f32_e32 v34, 1.0, v34
	v_add_f32_e32 v35, 1.0, v35
	v_add_f32_e32 v36, 1.0, v36
	v_add_f32_e32 v37, 1.0, v37
	v_add_f32_e32 v38, 1.0, v38
	v_add_f32_e32 v39, 1.0, v39
	v_add_f32_e32 v40, 1.0, v40
	v_add_f32_e32 v41, 1.0, v41
	v_add_f32_e32 v42, 1.0, v42
	v_add_f32_e32 v43, 1.0, v43
	v_add_f32_e32 v44, 1.0, v44
	v_add_f32_e32 v45, 1.0, v45
	v_add_f32_e32 v46, 1.0, v46
	v_add_f32_e32 v47, 1.0, v47
	v_rcp_f32_e32 v32, v32
	v_rcp_f32_e32 v33, v33
	v_rcp_f32_e32 v34, v34
	v_rcp_f32_e32 v35, v35
	v_rcp_f32_e32 v36, v36
	v_rcp_f32_e32 v37, v37
	v_rcp_f32_e32 v38, v38
	v_rcp_f32_e32 v39, v39
	v_rcp_f32_e32 v40, v40
	v_rcp_f32_e32 v41, v41
	v_rcp_f32_e32 v42, v42
	v_rcp_f32_e32 v43, v43
	v_rcp_f32_e32 v44, v44
	v_rcp_f32_e32 v45, v45
	v_rcp_f32_e32 v46, v46
	v_rcp_f32_e32 v47, v47
	s_nop 0
	v_mul_f32_e32 v32, v0, v32
	v_mul_f32_e32 v33, v1, v33
	v_mul_f32_e32 v34, v2, v34
	v_mul_f32_e32 v35, v3, v35
	v_mul_f32_e32 v36, v4, v36
	v_mul_f32_e32 v37, v5, v37
	v_mul_f32_e32 v38, v6, v38
	v_mul_f32_e32 v39, v7, v39
	v_mul_f32_e32 v40, v8, v40
	v_mul_f32_e32 v41, v9, v41
	v_mul_f32_e32 v42, v10, v42
	v_mul_f32_e32 v43, v11, v43
	v_mul_f32_e32 v44, v12, v44
	v_mul_f32_e32 v45, v13, v45
	v_mul_f32_e32 v46, v14, v46
	v_mul_f32_e32 v47, v15, v47
	v_mul_f32_e32 v32, v32, v16
	v_mul_f32_e32 v33, v33, v17
	v_mul_f32_e32 v34, v34, v18
	v_mul_f32_e32 v35, v35, v19
	v_mul_f32_e32 v36, v36, v20
	v_mul_f32_e32 v37, v37, v21
	v_mul_f32_e32 v38, v38, v22
	v_mul_f32_e32 v39, v39, v23
	v_mul_f32_e32 v40, v40, v24
	v_mul_f32_e32 v41, v41, v25
	v_mul_f32_e32 v42, v42, v26
	v_mul_f32_e32 v43, v43, v27
	v_mul_f32_e32 v44, v44, v28
	v_mul_f32_e32 v45, v45, v29
	v_mul_f32_e32 v46, v46, v30
	v_mul_f32_e32 v47, v47, v31
	v_cvt_pk_bf16_f32 v48, v32, v33
	v_cvt_pk_bf16_f32 v49, v34, v35
	v_cvt_pk_bf16_f32 v52, v36, v37
	v_cvt_pk_bf16_f32 v53, v38, v39
	v_cvt_pk_bf16_f32 v50, v40, v41
	v_cvt_pk_bf16_f32 v51, v42, v43
	v_cvt_pk_bf16_f32 v54, v44, v45
	v_cvt_pk_bf16_f32 v55, v46, v47
	s_nop 1
	v_permlane32_swap_b32_e32 v48, v50
	v_permlane32_swap_b32_e32 v49, v51
	v_permlane32_swap_b32_e32 v52, v54
	v_permlane32_swap_b32_e32 v53, v55
	s_nop 1
	global_store_dwordx4 v[66:67], v[48:51], off offset:64
	global_store_dwordx4 v[66:67], v[52:55], off offset:80
	v_accvgpr_read_b32 v68, a176
	v_accvgpr_read_b32 v69, a177
	v_accvgpr_read_b32 v70, a178
	v_accvgpr_read_b32 v71, a179
	v_accvgpr_read_b32 v72, a180
	v_accvgpr_read_b32 v73, a181
	v_accvgpr_read_b32 v74, a182
	v_accvgpr_read_b32 v75, a183
	v_accvgpr_read_b32 v76, a184
	v_accvgpr_read_b32 v77, a185
	v_accvgpr_read_b32 v78, a186
	v_accvgpr_read_b32 v79, a187
	v_accvgpr_read_b32 v80, a188
	v_accvgpr_read_b32 v81, a189
	v_accvgpr_read_b32 v82, a190
	v_accvgpr_read_b32 v83, a191
	v_mul_f32_e32 v138, 0xbfb8aa3b, v68
	v_mul_f32_e32 v139, 0xbfb8aa3b, v69
	v_mul_f32_e32 v140, 0xbfb8aa3b, v70
	v_mul_f32_e32 v141, 0xbfb8aa3b, v71
	v_mul_f32_e32 v142, 0xbfb8aa3b, v72
	v_mul_f32_e32 v143, 0xbfb8aa3b, v73
	v_mul_f32_e32 v144, 0xbfb8aa3b, v74
	v_mul_f32_e32 v145, 0xbfb8aa3b, v75
	v_mul_f32_e32 v146, 0xbfb8aa3b, v76
	v_mul_f32_e32 v147, 0xbfb8aa3b, v77
	v_mul_f32_e32 v148, 0xbfb8aa3b, v78
	v_mul_f32_e32 v149, 0xbfb8aa3b, v79
	v_mul_f32_e32 v150, 0xbfb8aa3b, v80
	v_mul_f32_e32 v151, 0xbfb8aa3b, v81
	v_mul_f32_e32 v152, 0xbfb8aa3b, v82
	v_mul_f32_e32 v153, 0xbfb8aa3b, v83
	v_accvgpr_read_b32 v104, a0
	v_accvgpr_read_b32 v105, a1
	v_accvgpr_read_b32 v106, a2
	v_accvgpr_read_b32 v107, a3
	v_accvgpr_read_b32 v108, a4
	v_accvgpr_read_b32 v109, a5
	v_accvgpr_read_b32 v110, a6
	v_accvgpr_read_b32 v111, a7
	v_accvgpr_read_b32 v112, a8
	v_accvgpr_read_b32 v113, a9
	v_accvgpr_read_b32 v114, a10
	v_accvgpr_read_b32 v115, a11
	v_accvgpr_read_b32 v116, a12
	v_accvgpr_read_b32 v117, a13
	v_accvgpr_read_b32 v118, a14
	v_accvgpr_read_b32 v119, a15
	v_exp_f32_e32 v138, v138
	v_exp_f32_e32 v139, v139
	v_exp_f32_e32 v140, v140
	v_exp_f32_e32 v141, v141
	v_exp_f32_e32 v142, v142
	v_exp_f32_e32 v143, v143
	v_exp_f32_e32 v144, v144
	v_exp_f32_e32 v145, v145
	v_exp_f32_e32 v146, v146
	v_exp_f32_e32 v147, v147
	v_exp_f32_e32 v148, v148
	v_exp_f32_e32 v149, v149
	v_exp_f32_e32 v150, v150
	v_exp_f32_e32 v151, v151
	v_exp_f32_e32 v152, v152
	v_exp_f32_e32 v153, v153
	s_nop 0
	v_add_f32_e32 v138, 1.0, v138
	v_add_f32_e32 v139, 1.0, v139
	v_add_f32_e32 v140, 1.0, v140
	v_add_f32_e32 v141, 1.0, v141
	v_add_f32_e32 v142, 1.0, v142
	v_add_f32_e32 v143, 1.0, v143
	v_add_f32_e32 v144, 1.0, v144
	v_add_f32_e32 v145, 1.0, v145
	v_add_f32_e32 v146, 1.0, v146
	v_add_f32_e32 v147, 1.0, v147
	v_add_f32_e32 v148, 1.0, v148
	v_add_f32_e32 v149, 1.0, v149
	v_add_f32_e32 v150, 1.0, v150
	v_add_f32_e32 v151, 1.0, v151
	v_add_f32_e32 v152, 1.0, v152
	v_add_f32_e32 v153, 1.0, v153
	v_rcp_f32_e32 v138, v138
	v_rcp_f32_e32 v139, v139
	v_rcp_f32_e32 v140, v140
	v_rcp_f32_e32 v141, v141
	v_rcp_f32_e32 v142, v142
	v_rcp_f32_e32 v143, v143
	v_rcp_f32_e32 v144, v144
	v_rcp_f32_e32 v145, v145
	v_rcp_f32_e32 v146, v146
	v_rcp_f32_e32 v147, v147
	v_rcp_f32_e32 v148, v148
	v_rcp_f32_e32 v149, v149
	v_rcp_f32_e32 v150, v150
	v_rcp_f32_e32 v151, v151
	v_rcp_f32_e32 v152, v152
	v_rcp_f32_e32 v153, v153
	s_nop 0
	v_mul_f32_e32 v138, v68, v138
	v_mul_f32_e32 v139, v69, v139
	v_mul_f32_e32 v140, v70, v140
	v_mul_f32_e32 v141, v71, v141
	v_mul_f32_e32 v142, v72, v142
	v_mul_f32_e32 v143, v73, v143
	v_mul_f32_e32 v144, v74, v144
	v_mul_f32_e32 v145, v75, v145
	v_mul_f32_e32 v146, v76, v146
	v_mul_f32_e32 v147, v77, v147
	v_mul_f32_e32 v148, v78, v148
	v_mul_f32_e32 v149, v79, v149
	v_mul_f32_e32 v150, v80, v150
	v_mul_f32_e32 v151, v81, v151
	v_mul_f32_e32 v152, v82, v152
	v_mul_f32_e32 v153, v83, v153
	v_mul_f32_e32 v138, v138, v104
	v_mul_f32_e32 v139, v139, v105
	v_mul_f32_e32 v140, v140, v106
	v_mul_f32_e32 v141, v141, v107
	v_mul_f32_e32 v142, v142, v108
	v_mul_f32_e32 v143, v143, v109
	v_mul_f32_e32 v144, v144, v110
	v_mul_f32_e32 v145, v145, v111
	v_mul_f32_e32 v146, v146, v112
	v_mul_f32_e32 v147, v147, v113
	v_mul_f32_e32 v148, v148, v114
	v_mul_f32_e32 v149, v149, v115
	v_mul_f32_e32 v150, v150, v116
	v_mul_f32_e32 v151, v151, v117
	v_mul_f32_e32 v152, v152, v118
	v_mul_f32_e32 v153, v153, v119
	v_cvt_pk_bf16_f32 v56, v138, v139
	v_cvt_pk_bf16_f32 v57, v140, v141
	v_cvt_pk_bf16_f32 v60, v142, v143
	v_cvt_pk_bf16_f32 v61, v144, v145
	v_cvt_pk_bf16_f32 v58, v146, v147
	v_cvt_pk_bf16_f32 v59, v148, v149
	v_cvt_pk_bf16_f32 v62, v150, v151
	v_cvt_pk_bf16_f32 v63, v152, v153
	s_nop 1
	v_permlane32_swap_b32_e32 v56, v58
	v_permlane32_swap_b32_e32 v57, v59
	v_permlane32_swap_b32_e32 v60, v62
	v_permlane32_swap_b32_e32 v61, v63
	s_nop 1
	global_store_dwordx4 v[64:65], v[56:59], off offset:64
	global_store_dwordx4 v[64:65], v[60:63], off offset:80
	s_mov_b32 s0, s98
	v_mov_b32_e32 v229, 0x4000
	v_mov_b32_e32 v214, 0x4000
	s_branch .LBB0_161
